# split seams: L2 writeback only where a cross-XCD read follows (ffn1down->inproj in layer 0)
# baseline (speedup 1.0000x reference)
.Lsp_noF_2:
	v_cmp_eq_u32_e32 vcc, 0, v1
	s_and_saveexec_b64 s[2:3], vcc
	s_cbranch_execz .LBB0_315
	v_readlane_b32 s100, v255, 40
	s_nop 3
	s_cmp_eq_u32 s100, 0
	s_cbranch_scc1 .Lfb_slow_2
	v_readlane_b32 s100, v255, 41
	v_readlane_b32 s101, v255, 42
	v_mov_b32_e32 v2, 0
	v_mov_b32_e32 v3, 1
	v_mov_b32_e32 v4, 1
	s_nop 2
	global_atomic_add v3, v2, v3, s[100:101] sc0
	s_waitcnt vmcnt(0)
	v_readfirstlane_b32 vcc_hi, v3
	s_nop 3
	s_lshr_b32 vcc_lo, vcc_hi, 5
	s_add_i32 vcc_hi, vcc_hi, 1
	s_and_b32 vcc_hi, vcc_hi, 31
	s_cmp_lg_u32 vcc_hi, 0
	s_cbranch_scc1 .Lfb_spin_2
	global_atomic_add v2, v4, s[100:101] offset:128
	v_readlane_b32 s100, v255, 12
	s_nop 3
	s_cmp_lg_u32 s100, 0
	s_cbranch_scc1 .Lsp_nowb_2
	buffer_wbl2 sc1
	s_waitcnt vmcnt(0)
.Lsp_nowb_2:
	v_readlane_b32 s100, v255, 45
	v_readlane_b32 s101, v255, 46
	s_nop 4
	global_atomic_add v2, v4, s[100:101]
	s_branch .Lfb_done_2

.Lsp_noF_8:
	v_cmp_eq_u32_e32 vcc, 0, v1
	s_and_saveexec_b64 s[2:3], vcc
	s_cbranch_execz .LBB0_1171
	v_readlane_b32 s100, v255, 40
	s_nop 3
	s_cmp_eq_u32 s100, 0
	s_cbranch_scc1 .Lfb_slow_8
	v_readlane_b32 s100, v255, 41
	v_readlane_b32 s101, v255, 42
	v_mov_b32_e32 v2, 0
	v_mov_b32_e32 v3, 1
	v_mov_b32_e32 v4, 1
	s_nop 2
	global_atomic_add v3, v2, v3, s[100:101] sc0
	s_waitcnt vmcnt(0)
	v_readfirstlane_b32 vcc_hi, v3
	s_nop 3
	s_lshr_b32 vcc_lo, vcc_hi, 5
	s_add_i32 vcc_hi, vcc_hi, 1
	s_and_b32 vcc_hi, vcc_hi, 31
	s_cmp_lg_u32 vcc_hi, 0
	s_cbranch_scc1 .Lfb_spin_8
	global_atomic_add v2, v4, s[100:101] offset:128
	v_readlane_b32 s100, v255, 45
	v_readlane_b32 s101, v255, 46
	s_nop 4
	global_atomic_add v2, v4, s[100:101]
	s_branch .Lfb_done_8
